# hyena unit: z and x0 row staging loops (global->LDS) unrolled x4 with all four loads in flight before the LDS writes, on top of v31
# baseline (speedup 1.0000x reference)
.LBB0_496:
	v_ashrrev_i32_e32 v83, 31, v2
	v_lshrrev_b32_e32 v83, 22, v83
	v_add_u32_e32 v83, v2, v83
	v_ashrrev_i32_e32 v88, 10, v83
	v_ashrrev_i32_e32 v89, 31, v88
	v_mul_i32_i24_e32 v83, 0x400, v88
	v_lshlrev_b64 v[84:85], 8, v[88:89]
	v_sub_u32_e32 v92, v2, v83
	v_lshlrev_b32_e32 v83, 3, v83
	v_lshl_add_u64 v[84:85], v[84:85], 0, s[2:3]
	v_mov_b64_e32 v[86:87], s[18:19]
	v_sub_u32_e32 v90, v0, v83
	v_mad_u64_u32 v[86:87], s[0:1], v84, s95, v[86:87]
	v_mad_i32_i24 v87, v85, s95, v87
	v_ashrrev_i32_e32 v91, 31, v90
	v_lshl_add_u64 v[84:85], v[90:91], 1, v[86:87]
	global_load_dwordx4 v[84:87], v[84:85], off offset:512
	v_mov_b32_e32 v83, s8
	v_mad_i32_i24 v83, v88, s9, v83
	v_lshrrev_b32_e32 v88, 3, v92
	v_and_b32_e32 v89, 56, v90
	v_mul_lo_u32 v88, v88, s57
	v_lshlrev_b32_e32 v89, 1, v89
	v_add3_u32 v83, v83, v88, v89
	v_add_u32_e32 v0, 0x1000, v0
	v_add_u32_e32 v2, 0x200, v2
	v_ashrrev_i32_e32 v95, 31, v2
	v_lshrrev_b32_e32 v95, 22, v95
	v_add_u32_e32 v95, v2, v95
	v_ashrrev_i32_e32 v100, 10, v95
	v_ashrrev_i32_e32 v101, 31, v100
	v_mul_i32_i24_e32 v95, 0x400, v100
	v_lshlrev_b64 v[96:97], 8, v[100:101]
	v_sub_u32_e32 v104, v2, v95
	v_lshlrev_b32_e32 v95, 3, v95
	v_lshl_add_u64 v[96:97], v[96:97], 0, s[2:3]
	v_mov_b64_e32 v[98:99], s[18:19]
	v_sub_u32_e32 v102, v0, v95
	v_mad_u64_u32 v[98:99], s[0:1], v96, s95, v[98:99]
	v_mad_i32_i24 v99, v97, s95, v99
	v_ashrrev_i32_e32 v103, 31, v102
	v_lshl_add_u64 v[96:97], v[102:103], 1, v[98:99]
	global_load_dwordx4 v[96:99], v[96:97], off offset:512
	v_mov_b32_e32 v95, s8
	v_mad_i32_i24 v95, v100, s9, v95
	v_lshrrev_b32_e32 v100, 3, v104
	v_and_b32_e32 v101, 56, v102
	v_mul_lo_u32 v100, v100, s57
	v_lshlrev_b32_e32 v101, 1, v101
	v_add3_u32 v95, v95, v100, v101
	v_add_u32_e32 v0, 0x1000, v0
	v_add_u32_e32 v2, 0x200, v2
	v_ashrrev_i32_e32 v107, 31, v2
	v_lshrrev_b32_e32 v107, 22, v107
	v_add_u32_e32 v107, v2, v107
	v_ashrrev_i32_e32 v112, 10, v107
	v_ashrrev_i32_e32 v113, 31, v112
	v_mul_i32_i24_e32 v107, 0x400, v112
	v_lshlrev_b64 v[108:109], 8, v[112:113]
	v_sub_u32_e32 v116, v2, v107
	v_lshlrev_b32_e32 v107, 3, v107
	v_lshl_add_u64 v[108:109], v[108:109], 0, s[2:3]
	v_mov_b64_e32 v[110:111], s[18:19]
	v_sub_u32_e32 v114, v0, v107
	v_mad_u64_u32 v[110:111], s[0:1], v108, s95, v[110:111]
	v_mad_i32_i24 v111, v109, s95, v111
	v_ashrrev_i32_e32 v115, 31, v114
	v_lshl_add_u64 v[108:109], v[114:115], 1, v[110:111]
	global_load_dwordx4 v[108:111], v[108:109], off offset:512
	v_mov_b32_e32 v107, s8
	v_mad_i32_i24 v107, v112, s9, v107
	v_lshrrev_b32_e32 v112, 3, v116
	v_and_b32_e32 v113, 56, v114
	v_mul_lo_u32 v112, v112, s57
	v_lshlrev_b32_e32 v113, 1, v113
	v_add3_u32 v107, v107, v112, v113
	v_add_u32_e32 v0, 0x1000, v0
	v_add_u32_e32 v2, 0x200, v2
	v_ashrrev_i32_e32 v119, 31, v2
	v_lshrrev_b32_e32 v119, 22, v119
	v_add_u32_e32 v119, v2, v119
	v_ashrrev_i32_e32 v124, 10, v119
	v_ashrrev_i32_e32 v125, 31, v124
	v_mul_i32_i24_e32 v119, 0x400, v124
	v_lshlrev_b64 v[120:121], 8, v[124:125]
	v_sub_u32_e32 v128, v2, v119
	v_lshlrev_b32_e32 v119, 3, v119
	v_lshl_add_u64 v[120:121], v[120:121], 0, s[2:3]
	v_mov_b64_e32 v[122:123], s[18:19]
	v_sub_u32_e32 v126, v0, v119
	v_mad_u64_u32 v[122:123], s[0:1], v120, s95, v[122:123]
	v_mad_i32_i24 v123, v121, s95, v123
	v_ashrrev_i32_e32 v127, 31, v126
	v_lshl_add_u64 v[120:121], v[126:127], 1, v[122:123]
	global_load_dwordx4 v[120:123], v[120:121], off offset:512
	v_mov_b32_e32 v119, s8
	v_mad_i32_i24 v119, v124, s9, v119
	v_lshrrev_b32_e32 v124, 3, v128
	v_and_b32_e32 v125, 56, v126
	v_mul_lo_u32 v124, v124, s57
	v_lshlrev_b32_e32 v125, 1, v125
	v_add3_u32 v119, v119, v124, v125
	v_add_u32_e32 v0, 0x1000, v0
	v_add_u32_e32 v2, 0x200, v2
	s_waitcnt vmcnt(3)
	ds_write_b128 v83, v[84:87] offset:2304
	s_waitcnt vmcnt(2)
	ds_write_b128 v95, v[96:99] offset:2304
	s_waitcnt vmcnt(1)
	ds_write_b128 v107, v[108:111] offset:2304
	s_waitcnt vmcnt(0)
	ds_write_b128 v119, v[120:123] offset:2304

.LBB0_506:
	v_ashrrev_i32_e32 v84, 31, v77
	v_lshrrev_b32_e32 v84, 22, v84
	v_add_u32_e32 v84, v77, v84
	v_ashrrev_i32_e32 v86, 10, v84
	v_ashrrev_i32_e32 v87, 31, v86
	v_mul_i32_i24_e32 v90, 0x400, v86
	v_lshlrev_b64 v[84:85], 8, v[86:87]
	v_mov_b64_e32 v[82:83], s[8:9]
	v_lshlrev_b32_e32 v88, 3, v90
	v_lshl_add_u64 v[84:85], v[84:85], 0, s[2:3]
	v_sub_u32_e32 v88, v76, v88
	v_mad_u64_u32 v[82:83], s[6:7], v84, s95, v[82:83]
	v_ashrrev_i32_e32 v89, 31, v88
	v_mad_i32_i24 v83, v85, s95, v83
	v_lshl_add_u64 v[82:83], v[88:89], 1, v[82:83]
	global_load_dwordx4 v[82:85], v[82:83], off offset:512
	v_add_u32_e32 v87, 0x200, v77
	v_mov_b32_e32 v77, v87
	v_lshlrev_b32_e32 v86, 14, v86
	v_lshlrev_b32_e32 v87, 4, v90
	v_sub_u32_e32 v86, v86, v87
	v_add_u32_e32 v76, 0x1000, v76
	v_add_u32_e32 v86, v0, v86
	v_add_u32_e32 v0, 0x2000, v0
	v_ashrrev_i32_e32 v96, 31, v77
	v_lshrrev_b32_e32 v96, 22, v96
	v_add_u32_e32 v96, v77, v96
	v_ashrrev_i32_e32 v98, 10, v96
	v_ashrrev_i32_e32 v99, 31, v98
	v_mul_i32_i24_e32 v102, 0x400, v98
	v_lshlrev_b64 v[96:97], 8, v[98:99]
	v_mov_b64_e32 v[94:95], s[8:9]
	v_lshlrev_b32_e32 v100, 3, v102
	v_lshl_add_u64 v[96:97], v[96:97], 0, s[2:3]
	v_sub_u32_e32 v100, v76, v100
	v_mad_u64_u32 v[94:95], s[6:7], v96, s95, v[94:95]
	v_ashrrev_i32_e32 v101, 31, v100
	v_mad_i32_i24 v95, v97, s95, v95
	v_lshl_add_u64 v[94:95], v[100:101], 1, v[94:95]
	global_load_dwordx4 v[94:97], v[94:95], off offset:512
	v_add_u32_e32 v99, 0x200, v77
	v_mov_b32_e32 v77, v99
	v_lshlrev_b32_e32 v98, 14, v98
	v_lshlrev_b32_e32 v99, 4, v102
	v_sub_u32_e32 v98, v98, v99
	v_add_u32_e32 v76, 0x1000, v76
	v_add_u32_e32 v98, v0, v98
	v_add_u32_e32 v0, 0x2000, v0
	v_ashrrev_i32_e32 v108, 31, v77
	v_lshrrev_b32_e32 v108, 22, v108
	v_add_u32_e32 v108, v77, v108
	v_ashrrev_i32_e32 v110, 10, v108
	v_ashrrev_i32_e32 v111, 31, v110
	v_mul_i32_i24_e32 v114, 0x400, v110
	v_lshlrev_b64 v[108:109], 8, v[110:111]
	v_mov_b64_e32 v[106:107], s[8:9]
	v_lshlrev_b32_e32 v112, 3, v114
	v_lshl_add_u64 v[108:109], v[108:109], 0, s[2:3]
	v_sub_u32_e32 v112, v76, v112
	v_mad_u64_u32 v[106:107], s[6:7], v108, s95, v[106:107]
	v_ashrrev_i32_e32 v113, 31, v112
	v_mad_i32_i24 v107, v109, s95, v107
	v_lshl_add_u64 v[106:107], v[112:113], 1, v[106:107]
	global_load_dwordx4 v[106:109], v[106:107], off offset:512
	v_add_u32_e32 v111, 0x200, v77
	v_mov_b32_e32 v77, v111
	v_lshlrev_b32_e32 v110, 14, v110
	v_lshlrev_b32_e32 v111, 4, v114
	v_sub_u32_e32 v110, v110, v111
	v_add_u32_e32 v76, 0x1000, v76
	v_add_u32_e32 v110, v0, v110
	v_add_u32_e32 v0, 0x2000, v0
	v_ashrrev_i32_e32 v120, 31, v77
	v_lshrrev_b32_e32 v120, 22, v120
	v_add_u32_e32 v120, v77, v120
	v_ashrrev_i32_e32 v122, 10, v120
	v_ashrrev_i32_e32 v123, 31, v122
	v_mul_i32_i24_e32 v126, 0x400, v122
	v_lshlrev_b64 v[120:121], 8, v[122:123]
	v_mov_b64_e32 v[118:119], s[8:9]
	v_lshlrev_b32_e32 v124, 3, v126
	v_lshl_add_u64 v[120:121], v[120:121], 0, s[2:3]
	v_sub_u32_e32 v124, v76, v124
	v_mad_u64_u32 v[118:119], s[6:7], v120, s95, v[118:119]
	v_ashrrev_i32_e32 v125, 31, v124
	v_mad_i32_i24 v119, v121, s95, v119
	v_lshl_add_u64 v[118:119], v[124:125], 1, v[118:119]
	global_load_dwordx4 v[118:121], v[118:119], off offset:512
	v_add_u32_e32 v123, 0x200, v77
	v_mov_b32_e32 v77, v123
	v_lshlrev_b32_e32 v122, 14, v122
	v_lshlrev_b32_e32 v123, 4, v126
	v_sub_u32_e32 v122, v122, v123
	v_add_u32_e32 v76, 0x1000, v76
	v_add_u32_e32 v122, v0, v122
	v_add_u32_e32 v0, 0x2000, v0
	s_waitcnt vmcnt(3)
	ds_write_b128 v86, v[82:85]
	s_waitcnt vmcnt(2)
	ds_write_b128 v98, v[94:97]
	s_waitcnt vmcnt(1)
	ds_write_b128 v110, v[106:109]
	s_waitcnt vmcnt(0)
	ds_write_b128 v122, v[118:121]
	s_branch .LBB0_472
